# MLA flash loop: V prefetch ring + exp/cvt interleaved with PV MFMAs, scalar counted vmcnt select, negm as direct C operand
# speedup vs baseline: 1.0355x; 1.0191x over previous
; #define MFMA(a, b, c) __builtin_amdgcn_mfma_f32_32x32x16_bf16((a), (b), (c), 0, 0, 0)
; DEV float fast_exp2(float x) { return __builtin_amdgcn_exp2f(x); }
; template <int DQK, int DV, int NKH, int MODE>
; DEV void flash_unit(const FlashArgs& fa, char* smem, f32x16 (&oacc)[DV / 32], float& linv_out) {
;     ...
;     {
;       const int newer = min(2, fa.n_tiles - 1 - it) * nld;
;       if (newer >= 8) asm volatile("s_waitcnt vmcnt(8)" ::: "memory");
;       else if (newer == 6) asm volatile("s_waitcnt vmcnt(6)" ::: "memory");
;       else if (newer == 4) asm volatile("s_waitcnt vmcnt(4)" ::: "memory");
;       else if (newer == 3) asm volatile("s_waitcnt vmcnt(3)" ::: "memory");
;       else if (newer == 2) asm volatile("s_waitcnt vmcnt(2)" ::: "memory");
;       else asm volatile("s_waitcnt vmcnt(0)" ::: "memory");
;     }
;     ...
;       float psum = 0.f;
; #pragma unroll
;       for (int k2 = 0; k2 < 2; ++k2)
; #pragma unroll
;         for (int e = 0; e < 16; ++e) { st[k2][e] = fast_exp2(st[k2][e]); psum += st[k2][e]; }
;       lrun += psum;
;       bf16x8 pf[2][2];
; #pragma unroll
;       for (int k2 = 0; k2 < 2; ++k2)
; #pragma unroll
;         for (int s2 = 0; s2 < 2; ++s2) {
;           uint4 u = make_uint4(pk2(st[k2][8 * s2], st[k2][8 * s2 + 1]), pk2(st[k2][8 * s2 + 2], st[k2][8 * s2 + 3]),
;                                pk2(st[k2][8 * s2 + 4], st[k2][8 * s2 + 5]), pk2(st[k2][8 * s2 + 6], st[k2][8 * s2 + 7]));
;           pf[k2][s2] = __builtin_bit_cast(bf16x8, u);
;         }
; #pragma unroll
;       for (int v = 0; v < NV; ++v)
; #pragma unroll
;         for (int k2 = 0; k2 < 2; ++k2)
; #pragma unroll
;           for (int s2 = 0; s2 < 2; ++s2) {
;             const char* a1 = vb + (k2 * 32 + s2 * 16) * VROW + vhi[v] + vlow0;
;             const char* a2 = vb + (k2 * 32 + s2 * 16 + 8) * VROW + vhi[v] + vlow1;
;             s16x4 lo = __builtin_amdgcn_ds_read_tr16_b64_v4i16((__attribute__((address_space(3))) s16x4*)(a1));
;             s16x4 hi = __builtin_amdgcn_ds_read_tr16_b64_v4i16((__attribute__((address_space(3))) s16x4*)(a2));
;             const bf16x8 vf = __builtin_shufflevector(lo, hi, 0, 1, 2, 3, 4, 5, 6, 7);
;             oacc[v] = MFMA(vf, pf[k2][s2], oacc[v]);
;           }
.LBB0_170:
	v_exp_f32_e32 v64, v64
	v_exp_f32_e32 v65, v65
	v_exp_f32_e32 v66, v66
	v_exp_f32_e32 v67, v67
	v_add_f32_e32 v120, v64, v65
	v_exp_f32_e32 v68, v68
	v_cvt_pk_bf16_f32 v64, v64, v65
	v_exp_f32_e32 v69, v69
	v_add_f32_e32 v120, v120, v66
	v_exp_f32_e32 v70, v70
	v_add_f32_e32 v120, v120, v67
	v_exp_f32_e32 v71, v71
	v_cvt_pk_bf16_f32 v65, v66, v67
	v_add_f32_e32 v120, v120, v68
	v_cvt_pk_bf16_f32 v66, v68, v69
	v_add_f32_e32 v120, v120, v69
	v_cvt_pk_bf16_f32 v67, v70, v71
	v_add_f32_e32 v120, v120, v70
	v_add_f32_e32 v120, v120, v71
	s_waitcnt lgkmcnt(6)
	v_mfma_f32_32x32x16_bf16 v[16:31], v[104:107], v[64:67], v[16:31]
	v_exp_f32_e32 v72, v72
	v_exp_f32_e32 v73, v73
	v_exp_f32_e32 v74, v74
	v_exp_f32_e32 v75, v75
	ds_read_b64_tr_b16 v[104:105], v122 offset:16384
	v_add_f32_e32 v120, v120, v72
	v_add_f32_e32 v120, v120, v73
	v_cvt_pk_bf16_f32 v72, v72, v73
	ds_read_b64_tr_b16 v[106:107], v122 offset:17408
	v_add_f32_e32 v120, v120, v74
	v_cvt_pk_bf16_f32 v73, v74, v75
	v_add_f32_e32 v120, v120, v75
	s_waitcnt lgkmcnt(6)
	v_mfma_f32_32x32x16_bf16 v[0:15], v[108:111], v[64:67], v[0:15]
	v_exp_f32_e32 v76, v76
	v_exp_f32_e32 v77, v77
	v_exp_f32_e32 v78, v78
	v_exp_f32_e32 v79, v79
	ds_read_b64_tr_b16 v[108:109], v123 offset:16384
	v_add_f32_e32 v120, v120, v76
	v_add_f32_e32 v120, v120, v77
	v_cvt_pk_bf16_f32 v74, v76, v77
	ds_read_b64_tr_b16 v[110:111], v123 offset:17408
	v_add_f32_e32 v120, v120, v78
	v_cvt_pk_bf16_f32 v75, v78, v79
	v_add_f32_e32 v120, v120, v79
	s_waitcnt lgkmcnt(6)
	v_mfma_f32_32x32x16_bf16 v[16:31], v[112:115], v[72:75], v[16:31]
	v_exp_f32_e32 v48, v48
	v_exp_f32_e32 v49, v49
	v_exp_f32_e32 v50, v50
	v_exp_f32_e32 v51, v51
	ds_read_b64_tr_b16 v[112:113], v122 offset:18432
	v_add_f32_e32 v120, v120, v48
	v_add_f32_e32 v120, v120, v49
	v_cvt_pk_bf16_f32 v48, v48, v49
	ds_read_b64_tr_b16 v[114:115], v122 offset:19456
	v_add_f32_e32 v120, v120, v50
	v_cvt_pk_bf16_f32 v49, v50, v51
	v_add_f32_e32 v120, v120, v51
	s_waitcnt lgkmcnt(6)
	v_mfma_f32_32x32x16_bf16 v[0:15], v[116:119], v[72:75], v[0:15]
	v_exp_f32_e32 v52, v52
	v_exp_f32_e32 v53, v53
	v_exp_f32_e32 v54, v54
	v_exp_f32_e32 v55, v55
	ds_read_b64_tr_b16 v[116:117], v123 offset:18432
	v_add_f32_e32 v120, v120, v52
	v_add_f32_e32 v120, v120, v53
	v_cvt_pk_bf16_f32 v50, v52, v53
	ds_read_b64_tr_b16 v[118:119], v123 offset:19456
	v_add_f32_e32 v120, v120, v54
	v_cvt_pk_bf16_f32 v51, v54, v55
	v_add_f32_e32 v120, v120, v55
	s_waitcnt lgkmcnt(6)
	v_mfma_f32_32x32x16_bf16 v[16:31], v[104:107], v[48:51], v[16:31]
	v_exp_f32_e32 v56, v56
	v_exp_f32_e32 v57, v57
	v_exp_f32_e32 v58, v58
	v_exp_f32_e32 v59, v59
	v_add_f32_e32 v120, v120, v56
	v_add_f32_e32 v120, v120, v57
	v_cvt_pk_bf16_f32 v56, v56, v57
	v_add_f32_e32 v120, v120, v58
	v_cvt_pk_bf16_f32 v57, v58, v59
	v_add_f32_e32 v120, v120, v59
	s_waitcnt lgkmcnt(4)
	v_mfma_f32_32x32x16_bf16 v[0:15], v[108:111], v[48:51], v[0:15]
	v_exp_f32_e32 v60, v60
	v_exp_f32_e32 v61, v61
	v_exp_f32_e32 v62, v62
	v_exp_f32_e32 v63, v63
	v_add_f32_e32 v120, v120, v60
	v_add_f32_e32 v120, v120, v61
	v_cvt_pk_bf16_f32 v58, v60, v61
	v_add_f32_e32 v120, v120, v62
	v_cvt_pk_bf16_f32 v59, v62, v63
	v_add_f32_e32 v120, v120, v63
	s_waitcnt lgkmcnt(2)
	v_mfma_f32_32x32x16_bf16 v[16:31], v[112:115], v[56:59], v[16:31]
	v_add_f32_e32 v134, v134, v120
	v_lshl_add_u64 v[136:137], v[136:137], 0, v[132:133]
	v_lshl_add_u64 v[138:139], v[138:139], 0, v[130:131]
	v_lshl_add_u64 v[140:141], v[140:141], 0, v[128:129]
	s_add_i32 s20, s20, -1
	s_add_i32 s19, s19, 1
	s_waitcnt lgkmcnt(0)
	v_mfma_f32_32x32x16_bf16 v[0:15], v[116:119], v[56:59], v[0:15]
	s_cmp_lg_u32 s20, -1
	s_cbranch_scc0 .LBB0_128
.LBB0_171:
	s_cmp_lt_i32 s20, 2
	s_cbranch_scc1 .Lmla_wait0
	s_and_b64 vcc, exec, s[38:39]
	s_cbranch_vccnz .Lmla_wait4
	s_waitcnt vmcnt(6)
	s_branch .Lmla_waitd
.Lmla_wait4:
	s_waitcnt vmcnt(4)
	s_branch .Lmla_waitd

; #define MFMA(a, b, c) __builtin_amdgcn_mfma_f32_32x32x16_bf16((a), (b), (c), 0, 0, 0)
; template <int DQK, int DV, int NKH, int MODE>
; DEV void flash_unit(const FlashArgs& fa, char* smem, f32x16 (&oacc)[DV / 32], float& linv_out) {
;     ...
;       const char* sb = smem + (it & (NSTG - 1)) * STAGE;
;       const char* kb = sb + kh * 8192 + r * 128;
;       const char* kb32 = sb + OFF_K32 + r * 64;
;       const char* vb = sb + OFF_V;
;       f32x16 st[2];
;       bf16x8 kfr[2][NS];
; #pragma unroll
;       for (int k2 = 0; k2 < 2; ++k2)
; #pragma unroll
;         for (int s = 0; s < NS; ++s) {
;           if (s < 4) kfr[k2][s] = *(const bf16x8*)(kb + k2 * 32 * 128 + kxo[s]);
;           else kfr[k2][s] = *(const bf16x8*)(kb32 + k2 * 32 * 64 + (((2 * (s - 4) + h) ^ k32x) << 4));
;         }
;       __builtin_amdgcn_sched_barrier(0);
; #pragma unroll
;       for (int k2 = 0; k2 < 2; ++k2) {
; #pragma unroll
;         for (int s = 0; s < NS; ++s) {
;           const bf16x8 kf = kfr[k2][s];
;           if (s == 0) st[k2] = MFMA(kf, qf[s], negm);
;           else st[k2] = MFMA(kf, qf[s], st[k2]);
;           constexpr int NQK = 2 * NS, EVERY = NQK / LPT;
;           const int m = k2 * NS + s;
;           if ((m + 1) % EVERY == 0 && (m + 1) / EVERY <= LPT) {
;             __builtin_amdgcn_sched_barrier(0);
;             if (pre) issue_piece(it + 3, (m + 1) / EVERY - 1);
;             __builtin_amdgcn_sched_barrier(0);
;           }
;         }
;       }
.Lmla_waitd:
	s_add_i32 s2, s19, -3
	s_and_b32 s2, s2, 3
	s_mulk_i32 s2, 0x5000
	s_add_i32 s6, s2, 0
	v_add_u32_e32 v48, s6, v146
	v_add_u32_e32 v49, s6, v148
	v_add_u32_e32 v50, v48, v151
	v_add_u32_e32 v51, v48, v152
	v_add_u32_e32 v52, v48, v153
	v_add_u32_e32 v48, v48, v154
	v_add_u32_e32 v53, v49, v149
	s_barrier
	v_add_u32_e32 v64, v49, v150
	ds_read_b128 v[56:59], v50
	ds_read_b128 v[120:123], v50 offset:4096
	ds_read_b128 v[60:63], v51
	ds_read_b128 v[124:127], v51 offset:4096
	ds_read_b128 v[160:163], v52
	ds_read_b128 v[104:107], v52 offset:4096
	ds_read_b128 v[182:185], v48
	ds_read_b128 v[108:111], v48 offset:4096
	ds_read_b128 v[48:51], v53 offset:8192
	ds_read_b128 v[112:115], v53 offset:10240
	ds_read_b128 v[52:55], v64 offset:8192
	ds_read_b128 v[116:119], v64 offset:10240
	s_cmp_ge_u32 s19, s18
	s_cselect_b64 s[2:3], -1, 0
	s_cmp_lt_u32 s19, s18
	s_cselect_b64 s[4:5], -1, 0
	s_waitcnt lgkmcnt(11)
	v_mfma_f32_32x32x16_bf16 v[64:79], v[56:59], v[80:83], v[32:47]
	s_and_b32 s7, s19, 3
	s_mulk_i32 s7, 0x5000
	s_waitcnt lgkmcnt(9)
	v_mfma_f32_32x32x16_bf16 v[64:79], v[60:63], v[84:87], v[64:79]
	s_waitcnt lgkmcnt(7)
	v_mfma_f32_32x32x16_bf16 v[64:79], v[160:163], v[88:91], v[64:79]
	s_waitcnt lgkmcnt(5)
	v_mfma_f32_32x32x16_bf16 v[64:79], v[182:185], v[92:95], v[64:79]
	s_and_b64 vcc, exec, s[2:3]
	v_add_u32_e32 v144, s7, v143
	s_cbranch_vccnz .LBB0_191
	v_readfirstlane_b32 s7, v144
	s_mov_b32 m0, s7
	s_nop 0
	global_load_lds_dwordx4 v[140:141], off
.LBB0_191:
	s_waitcnt lgkmcnt(0)
	v_mfma_f32_32x32x16_bf16 v[64:79], v[48:51], v[96:99], v[64:79]
	v_mfma_f32_32x32x16_bf16 v[64:79], v[52:55], v[100:103], v[64:79]
	v_mfma_f32_32x32x16_bf16 v[48:63], v[120:123], v[80:83], v[32:47]
	v_mfma_f32_32x32x16_bf16 v[48:63], v[124:127], v[84:87], v[48:63]
	s_andn2_b64 vcc, exec, s[4:5]
	s_cbranch_vccnz .LBB0_193
	v_add_u32_e32 v120, 0x2000, v144
	s_nop 0
	v_readfirstlane_b32 s4, v120
	s_mov_b32 m0, s4
	s_nop 0
	global_load_lds_dwordx4 v[138:139], off

; DEV float fast_exp2(float x) { return __builtin_amdgcn_exp2f(x); }
; template <int DQK, int DV, int NKH, int MODE>
; DEV void flash_unit(const FlashArgs& fa, char* smem, f32x16 (&oacc)[DV / 32], float& linv_out) {
;     ...
;       float rel = st[0][0];
; #pragma unroll
;       for (int e = 1; e < 16; ++e) rel = fmaxf(rel, st[0][e]);
; #pragma unroll
;       for (int e = 0; e < 16; ++e) rel = fmaxf(rel, st[1][e]);
;       rel = half_max(rel);
;       const bool first = (it == 0);
;       if (first || __builtin_amdgcn_ballot_w64(rel > 8.f) != 0) {
;         const float d = first ? rel : fmaxf(rel, 0.f);
;         const float alpha = fast_exp2(-d);
;         mrun += d;
; #pragma unroll
;         for (int k2 = 0; k2 < 2; ++k2)
; #pragma unroll
;           for (int e = 0; e < 16; ++e) st[k2][e] -= d;
; #pragma unroll
;         for (int v = 0; v < NV; ++v)
; #pragma unroll
;           for (int e = 0; e < 16; ++e) oacc[v][e] *= alpha;
; #pragma unroll
;         for (int e = 0; e < 16; ++e) negm[e] = -mrun;
;         lrun *= alpha;
;       }
;     ...
;             const char* a1 = vb + (k2 * 32 + s2 * 16) * VROW + vhi[v] + vlow0;
;             const char* a2 = vb + (k2 * 32 + s2 * 16 + 8) * VROW + vhi[v] + vlow1;
;             s16x4 lo = __builtin_amdgcn_ds_read_tr16_b64_v4i16((__attribute__((address_space(3))) s16x4*)(a1));
;             s16x4 hi = __builtin_amdgcn_ds_read_tr16_b64_v4i16((__attribute__((address_space(3))) s16x4*)(a2));
.LBB0_195:
	s_or_b64 exec, exec, s[2:3]
	v_add3_u32 v122, s6, v156, v158
	v_add3_u32 v123, s6, v157, v158
	ds_read_b64_tr_b16 v[104:105], v122 offset:12288
	ds_read_b64_tr_b16 v[106:107], v122 offset:13312
	ds_read_b64_tr_b16 v[108:109], v123 offset:12288
	ds_read_b64_tr_b16 v[110:111], v123 offset:13312
	ds_read_b64_tr_b16 v[112:113], v122 offset:14336
	ds_read_b64_tr_b16 v[114:115], v122 offset:15360
	ds_read_b64_tr_b16 v[116:117], v123 offset:14336
	ds_read_b64_tr_b16 v[118:119], v123 offset:15360
	v_max3_f32 v144, v64, v65, v66
	v_max3_f32 v144, v144, v67, v68
	v_max3_f32 v144, v144, v69, v70
	v_max3_f32 v144, v144, v71, v72
	v_max3_f32 v144, v144, v73, v74
	v_max3_f32 v144, v144, v75, v76
	v_max3_f32 v144, v144, v77, v78
	v_max3_f32 v144, v144, v79, v48
	v_max3_f32 v144, v144, v49, v50
	v_max3_f32 v144, v144, v51, v52
	v_max3_f32 v144, v144, v53, v54
	v_max3_f32 v144, v144, v55, v56
	v_max3_f32 v144, v144, v57, v58
	v_max3_f32 v144, v144, v59, v60
	v_max3_f32 v144, v144, v61, v62
	v_max_f32_e32 v144, v144, v63
	v_mov_b32_e32 v121, v144
	s_nop 1
	v_permlane32_swap_b32_e32 v144, v121
	v_max_f32_e32 v144, v144, v121
	v_cmp_lt_f32_e32 vcc, s33, v144
	s_cbranch_vccz .LBB0_170
	v_max_f32_e32 v32, v144, v144
	v_max_f32_e32 v32, 0, v32
	v_exp_f32_e64 v34, -v32
	v_add_f32_e32 v135, v135, v32
	v_pk_add_f32 v[64:65], v[64:65], v[32:33] op_sel_hi:[1,0] neg_lo:[0,1] neg_hi:[0,1]
	v_pk_add_f32 v[66:67], v[66:67], v[32:33] op_sel_hi:[1,0] neg_lo:[0,1] neg_hi:[0,1]
	v_pk_add_f32 v[68:69], v[68:69], v[32:33] op_sel_hi:[1,0] neg_lo:[0,1] neg_hi:[0,1]
	v_pk_add_f32 v[70:71], v[70:71], v[32:33] op_sel_hi:[1,0] neg_lo:[0,1] neg_hi:[0,1]
	v_pk_add_f32 v[72:73], v[72:73], v[32:33] op_sel_hi:[1,0] neg_lo:[0,1] neg_hi:[0,1]
	v_pk_add_f32 v[74:75], v[74:75], v[32:33] op_sel_hi:[1,0] neg_lo:[0,1] neg_hi:[0,1]
	v_pk_add_f32 v[76:77], v[76:77], v[32:33] op_sel_hi:[1,0] neg_lo:[0,1] neg_hi:[0,1]
	v_pk_add_f32 v[78:79], v[78:79], v[32:33] op_sel_hi:[1,0] neg_lo:[0,1] neg_hi:[0,1]
	v_pk_add_f32 v[48:49], v[48:49], v[32:33] op_sel_hi:[1,0] neg_lo:[0,1] neg_hi:[0,1]
	v_pk_add_f32 v[50:51], v[50:51], v[32:33] op_sel_hi:[1,0] neg_lo:[0,1] neg_hi:[0,1]
	v_pk_add_f32 v[52:53], v[52:53], v[32:33] op_sel_hi:[1,0] neg_lo:[0,1] neg_hi:[0,1]
	v_pk_add_f32 v[54:55], v[54:55], v[32:33] op_sel_hi:[1,0] neg_lo:[0,1] neg_hi:[0,1]
	v_pk_add_f32 v[56:57], v[56:57], v[32:33] op_sel_hi:[1,0] neg_lo:[0,1] neg_hi:[0,1]
	v_pk_add_f32 v[58:59], v[58:59], v[32:33] op_sel_hi:[1,0] neg_lo:[0,1] neg_hi:[0,1]
	v_pk_add_f32 v[60:61], v[60:61], v[32:33] op_sel_hi:[1,0] neg_lo:[0,1] neg_hi:[0,1]
	v_pk_add_f32 v[62:63], v[62:63], v[32:33] op_sel_hi:[1,0] neg_lo:[0,1] neg_hi:[0,1]
	v_xor_b32_e32 v32, 0x80000000, v135
	v_pk_mul_f32 v[14:15], v[14:15], v[34:35] op_sel_hi:[1,0]
	v_pk_mul_f32 v[12:13], v[12:13], v[34:35] op_sel_hi:[1,0]
	v_pk_mul_f32 v[10:11], v[10:11], v[34:35] op_sel_hi:[1,0]
	v_pk_mul_f32 v[8:9], v[8:9], v[34:35] op_sel_hi:[1,0]
	v_pk_mul_f32 v[6:7], v[6:7], v[34:35] op_sel_hi:[1,0]
	v_pk_mul_f32 v[4:5], v[4:5], v[34:35] op_sel_hi:[1,0]
	v_pk_mul_f32 v[2:3], v[2:3], v[34:35] op_sel_hi:[1,0]
	v_pk_mul_f32 v[0:1], v[0:1], v[34:35] op_sel_hi:[1,0]
	v_pk_mul_f32 v[30:31], v[30:31], v[34:35] op_sel_hi:[1,0]
	v_pk_mul_f32 v[28:29], v[28:29], v[34:35] op_sel_hi:[1,0]
	v_pk_mul_f32 v[26:27], v[26:27], v[34:35] op_sel_hi:[1,0]
	v_pk_mul_f32 v[24:25], v[24:25], v[34:35] op_sel_hi:[1,0]
	v_pk_mul_f32 v[22:23], v[22:23], v[34:35] op_sel_hi:[1,0]
	v_pk_mul_f32 v[20:21], v[20:21], v[34:35] op_sel_hi:[1,0]
	v_pk_mul_f32 v[18:19], v[18:19], v[34:35] op_sel_hi:[1,0]
	v_pk_mul_f32 v[16:17], v[16:17], v[34:35] op_sel_hi:[1,0]
	v_mul_f32_e32 v134, v134, v34
	v_mov_b32_e32 v33, v32
	v_mov_b32_e32 v34, v32
	v_mov_b32_e32 v35, v32
	v_mov_b32_e32 v36, v32
	v_mov_b32_e32 v37, v32
	v_mov_b32_e32 v38, v32
	v_mov_b32_e32 v39, v32
	v_mov_b32_e32 v40, v32
	v_mov_b32_e32 v41, v32
	v_mov_b32_e32 v42, v32
	v_mov_b32_e32 v43, v32
	v_mov_b32_e32 v44, v32
	v_mov_b32_e32 v45, v32
	v_mov_b32_e32 v46, v32
	v_mov_b32_e32 v47, v32
	s_branch .LBB0_170
